# stack v64 + hgrn log(max(f,1e-30)): the never-taken denormal rescale and is-finite selects around v_log_f32 removed (argument clamped above FLT_MIN; bit-identical)
# speedup vs baseline: 1.0073x; 1.0073x over previous
; #define LAS __attribute__((address_space(3)))
; __device__ __forceinline__ unsigned pk2(float lo, float hi) { unsigned r; asm("v_cvt_pk_bf16_f32 %0, %1, %2" : "=v"(r) : "v"(lo), "v"(hi)); return r; }
; __device__ __forceinline__ float fexp(float x) { return __builtin_amdgcn_exp2f(x * LOG2E); }
; __device__ __forceinline__ float sigm(float x) { return frcp(1.f + fexp(-x)); }
; __device__ __forceinline__ void lds_barrier() { asm volatile("s_waitcnt lgkmcnt(0)" ::: "memory"); __builtin_amdgcn_s_barrier(); asm volatile("" ::: "memory"); }
; #define HG_LOAD(n_) do { const size_t T0_ = (size_t)b * SEQ + seg * 128 + (n_) * 16; \
;         _Pragma("unroll") for (int j = 0; j < 4; ++j) { const bf16_t* zp = p.z + (T0_ + fq * 4 + j) * ZLD; qn[j] = zp[768 + kch]; fn[j] = zp[1024 + kch]; vn[j] = zp[1280 + kch]; } } while (0)
; __device__ __forceinline__ void hgrn_item(const Params& p, int l, int item, int pass, LAS unsigned char* lds) {
;     ...
;         if (n < 7) HG_LOAD(n + 1);
;         u32x4 vw; vw.x = vv[0] | (vv[1] << 16); vw.y = vv[2] | (vv[3] << 16); vw.z = 0u; vw.w = 0u; const bf16x8 vfrag = as_bf8(vw);
;         float cs[4], kf[4]; float run = 0.f;
; #pragma unroll
;         for (int j = 0; j < 4; ++j) { const float sg = sigm(fz[j]); const float f = lbv + (1.f - lbv) * sg; run += __logf(fmaxf(f, 1e-30f)); cs[j] = run; kf[j] = (1.f - lbv) * sigm(-fz[j]); }
;         { const float t1 = __shfl(run, lane - 16), t2 = __shfl(run, lane - 32), t3 = __shfl(run, lane - 48);
;           const float pre = (fq >= 1 ? t1 : 0.f) + (fq >= 2 ? t2 : 0.f) + (fq >= 3 ? t3 : 0.f);
; #pragma unroll
;           for (int j = 0; j < 4; ++j) cs[j] += pre; }
;         const float blast = __shfl(cs[3], 48 + fr);
;         lds_barrier();
;         { u32x2 w; w.x = pk2(kf[0] * fexp(blast - cs[0]), kf[1] * fexp(blast - cs[1])); w.y = pk2(kf[2] * fexp(blast - cs[2]), kf[3] * fexp(blast - cs[3]));
;           *(LAS u32x2*)(KHt + (wv * 16 + fr) * 16 + fq * 4) = w;
;           if (fq == 0) decs[wv * 16 + fr] = fexp(blast);
.LBB0_334:
	v_lshl_add_u64 v[0:1], v[42:43], 0, s[70:71]
	v_add_co_u32_e64 v24, s[18:19], s38, v0
	s_waitcnt vmcnt(10)
	v_lshlrev_b32_e32 v26, 16, v78
	v_addc_co_u32_e64 v25, s[18:19], 0, v1, s[18:19]
	global_load_ushort v20, v[24:25], off offset:1536
	global_load_ushort v22, v[24:25], off offset:2048
	global_load_ushort v28, v[24:25], off offset:2560
	v_add_co_u32_e64 v24, s[18:19], s23, v0
	s_waitcnt vmcnt(7)
	v_lshlrev_b32_e32 v78, 16, v71
	v_addc_co_u32_e64 v25, s[18:19], 0, v1, s[18:19]
	global_load_ushort v30, v[24:25], off offset:3072
	global_load_ushort v70, v[24:25], off offset:3584
	v_add_co_u32_e64 v24, s[18:19], s83, v0
	v_lshlrev_b32_e32 v27, 16, v79
	s_nop 0
	v_addc_co_u32_e64 v25, s[18:19], 0, v1, s[18:19]
	global_load_ushort v71, v[24:25], off
	v_add_co_u32_e64 v24, s[18:19], s33, v0
	s_waitcnt vmcnt(7)
	v_lshlrev_b32_e32 v79, 16, v72
	v_addc_co_u32_e64 v25, s[18:19], 0, v1, s[18:19]
	v_add_co_u32_e64 v0, s[18:19], s22, v0
	global_load_ushort v72, v[24:25], off offset:512
	global_load_ushort v73, v[24:25], off offset:1024
	global_load_ushort v74, v[24:25], off offset:1536
	v_addc_co_u32_e64 v1, s[18:19], 0, v1, s[18:19]
	global_load_ushort v75, v[0:1], off offset:2048
	global_load_ushort v76, v[0:1], off offset:2560
	global_load_ushort v77, v[0:1], off offset:3072
	v_lshl_add_u64 v[104:105], v[40:41], 0, s[70:71]
	global_load_dwordx2 v[102:103], v[104:105], off
	v_mul_f32_e32 v0, 0xbfb8aa3b, v26
	v_exp_f32_e32 v0, v0
	s_waitcnt lgkmcnt(0)
	s_barrier
	v_add_f32_e32 v0, 1.0, v0
	v_rcp_f32_e32 v0, v0
	s_nop 0
	v_fma_f32 v0, v56, v0, v47
	v_max_f32_e32 v0, 0xda24260, v0
	s_nop 1
	v_log_f32_e32 v0, v0
	s_nop 0
	v_mul_f32_e32 v1, 0x3f317217, v0
	v_fma_f32 v1, v0, s85, -v1
	v_fmac_f32_e32 v1, 0x3377d1cf, v0
	v_fmac_f32_e32 v1, 0x3f317217, v0
	s_nop 1
	v_mov_b32_e32 v0, v1
	v_mul_f32_e32 v1, 0x3fb8aa3b, v26
	v_exp_f32_e32 v1, v1
	v_mul_f32_e32 v26, 0xbfb8aa3b, v78
	v_exp_f32_e32 v26, v26
	v_add_f32_e32 v0, 0, v0
	v_add_f32_e32 v1, 1.0, v1
	v_rcp_f32_e32 v1, v1
	v_add_f32_e32 v26, 1.0, v26
	v_rcp_f32_e32 v26, v26
	v_mul_f32_e32 v24, v56, v1
	v_mul_f32_e32 v1, 0xbfb8aa3b, v27
	v_exp_f32_e32 v1, v1
	v_fma_f32 v26, v56, v26, v47
	v_max_f32_e32 v26, 0xda24260, v26
	v_add_f32_e32 v1, 1.0, v1
	v_rcp_f32_e32 v1, v1
	s_nop 0
	v_fma_f32 v1, v56, v1, v47
	v_max_f32_e32 v1, 0xda24260, v1
	s_nop 1
	v_log_f32_e32 v1, v1
	s_nop 0
	v_mul_f32_e32 v25, 0x3f317217, v1
	v_fma_f32 v25, v1, s85, -v25
	v_fmac_f32_e32 v25, 0x3377d1cf, v1
	v_fmac_f32_e32 v25, 0x3f317217, v1
	s_nop 1
	v_mov_b32_e32 v1, v25
	v_mul_f32_e32 v25, 0x3fb8aa3b, v27
	v_log_f32_e32 v26, v26
	v_add_f32_e32 v1, v1, v0
	v_exp_f32_e32 v25, v25
	v_mul_f32_e32 v27, 0x3f317217, v26
	v_fma_f32 v27, v26, s85, -v27
	v_fmac_f32_e32 v27, 0x3377d1cf, v26
	v_fmac_f32_e32 v27, 0x3f317217, v26
	v_add_f32_e32 v25, 1.0, v25
	v_rcp_f32_e32 v25, v25
	v_mov_b32_e32 v26, v27
	v_mul_f32_e32 v27, 0xbfb8aa3b, v79
	v_exp_f32_e32 v27, v27
	v_add_f32_e32 v82, v26, v1
	v_mul_f32_e32 v26, 0x3fb8aa3b, v78
	v_exp_f32_e32 v26, v26
	v_add_f32_e32 v27, 1.0, v27
	v_rcp_f32_e32 v27, v27
	v_mul_f32_e32 v25, v56, v25
	v_add_f32_e32 v26, 1.0, v26
	v_rcp_f32_e32 v26, v26
	v_fma_f32 v27, v56, v27, v47
	v_max_f32_e32 v27, 0xda24260, v27
	v_mul_f32_e32 v26, v56, v26
	s_nop 0
	v_log_f32_e32 v27, v27
	s_nop 0
	v_mul_f32_e32 v78, 0x3f317217, v27
	v_fma_f32 v78, v27, s85, -v78
	v_fmac_f32_e32 v78, 0x3377d1cf, v27
	v_fmac_f32_e32 v78, 0x3f317217, v27
	s_nop 1
	v_mov_b32_e32 v27, v78
	v_add_f32_e32 v78, v27, v82
	v_mul_f32_e32 v27, 0x3fb8aa3b, v79
	ds_bpermute_b32 v79, v54, v78
	ds_bpermute_b32 v80, v55, v78
	ds_bpermute_b32 v81, v58, v78
	v_exp_f32_e32 v27, v27
	s_waitcnt lgkmcnt(2)
	v_cndmask_b32_e64 v79, v79, 0, vcc
	s_waitcnt lgkmcnt(1)
	v_cndmask_b32_e64 v80, 0, v80, s[12:13]
	v_add_f32_e32 v79, v79, v80
	s_waitcnt lgkmcnt(0)
	v_cndmask_b32_e64 v80, 0, v81, s[14:15]
	v_add_f32_e32 v83, v79, v80
	v_add_f32_e32 v78, v78, v83
	v_add_f32_e32 v81, v0, v83
	ds_bpermute_b32 v0, v57, v78
	v_add_f32_e32 v80, v1, v83
	v_add_f32_e32 v79, v82, v83
	v_add_f32_e32 v27, 1.0, v27
	v_rcp_f32_e32 v27, v27
	s_waitcnt lgkmcnt(0)
	v_sub_f32_e32 v1, v0, v81
	v_sub_f32_e32 v82, v0, v80
	v_mul_f32_e32 v1, 0x3fb8aa3b, v1
	v_mul_f32_e32 v82, 0x3fb8aa3b, v82
	v_exp_f32_e32 v1, v1
	v_exp_f32_e32 v82, v82
	v_sub_f32_e32 v83, v0, v78
	v_mul_f32_e32 v83, 0x3fb8aa3b, v83
	v_mul_f32_e32 v1, v24, v1
	v_mul_f32_e32 v82, v25, v82
	v_cvt_pk_bf16_f32 v82, v1, v82
	v_sub_f32_e32 v1, v0, v79
	v_mul_f32_e32 v1, 0x3fb8aa3b, v1
	v_exp_f32_e32 v83, v83
	v_exp_f32_e32 v1, v1
	v_mul_f32_e32 v27, v56, v27
	v_mul_f32_e32 v83, v27, v83
	v_mul_f32_e32 v1, v26, v1
	v_cvt_pk_bf16_f32 v83, v1, v83
	ds_write_b64 v59, v[82:83] offset:4608
	s_and_saveexec_b64 s[18:19], vcc
	s_cbranch_execz .LBB0_336
	v_mul_f32_e32 v0, 0x3fb8aa3b, v0
	v_exp_f32_e32 v0, v0
	v_add_u32_e32 v1, v53, v60
	ds_write_b32 v1, v0 offset:6656

; #define LAS __attribute__((address_space(3)))
; __device__ __forceinline__ unsigned pk2(float lo, float hi) { unsigned r; asm("v_cvt_pk_bf16_f32 %0, %1, %2" : "=v"(r) : "v"(lo), "v"(hi)); return r; }
; __device__ __forceinline__ float fexp(float x) { return __builtin_amdgcn_exp2f(x * LOG2E); }
; __device__ __forceinline__ float sigm(float x) { return frcp(1.f + fexp(-x)); }
; __device__ __forceinline__ void lds_barrier() { asm volatile("s_waitcnt lgkmcnt(0)" ::: "memory"); __builtin_amdgcn_s_barrier(); asm volatile("" ::: "memory"); }
; __device__ __forceinline__ void hgrn_item(const Params& p, int l, int item, int pass, LAS unsigned char* lds) {
;     ...
;         for (int j = 0; j < 4; ++j) { const float sg = sigm(fz[j]); const float f = lbv + (1.f - lbv) * sg; run += __logf(fmaxf(f, 1e-30f)); cs[j] = run; kf[j] = (1.f - lbv) * sigm(-fz[j]); }
;         { const float t1 = __shfl(run, lane - 16), t2 = __shfl(run, lane - 32), t3 = __shfl(run, lane - 48);
;           const float pre = (fq >= 1 ? t1 : 0.f) + (fq >= 2 ? t2 : 0.f) + (fq >= 3 ? t3 : 0.f);
; #pragma unroll
;           for (int j = 0; j < 4; ++j) cs[j] += pre; }
;         const float blast = __shfl(cs[3], 48 + fr);
;         lds_barrier();
;         { u32x2 w; w.x = pk2(kf[0] * fexp(blast - cs[0]), kf[1] * fexp(blast - cs[1])); w.y = pk2(kf[2] * fexp(blast - cs[2]), kf[3] * fexp(blast - cs[3]));
;           *(LAS u32x2*)(KHt + (wv * 16 + fr) * 16 + fq * 4) = w;
;           if (fq == 0) decs[wv * 16 + fr] = fexp(blast);
.LBB0_338:
	v_lshlrev_b32_e32 v20, 16, v78
	v_mul_f32_e32 v24, 0xbfb8aa3b, v20
	v_exp_f32_e32 v24, v24
	v_lshlrev_b32_e32 v22, 16, v79
	v_lshlrev_b32_e32 v1, 16, v71
	v_lshlrev_b32_e32 v0, 16, v72
	v_add_f32_e32 v24, 1.0, v24
	v_rcp_f32_e32 v24, v24
	v_mul_f32_e32 v20, 0x3fb8aa3b, v20
	v_exp_f32_e32 v20, v20
	s_waitcnt lgkmcnt(0)
	v_fma_f32 v24, v56, v24, v47
	v_max_f32_e32 v24, 0xda24260, v24
	v_add_f32_e32 v20, 1.0, v20
	v_rcp_f32_e32 v20, v20
	v_log_f32_e32 v24, v24
	v_mul_f32_e32 v20, v56, v20
	s_barrier
	v_mul_f32_e32 v25, 0x3f317217, v24
	v_fma_f32 v25, v24, s85, -v25
	v_fmac_f32_e32 v25, 0x3377d1cf, v24
	v_fmac_f32_e32 v25, 0x3f317217, v24
	s_nop 1
	v_mov_b32_e32 v24, v25
	v_add_f32_e32 v25, 0, v24
	v_mul_f32_e32 v24, 0xbfb8aa3b, v22
	v_exp_f32_e32 v24, v24
	v_mul_f32_e32 v22, 0x3fb8aa3b, v22
	v_exp_f32_e32 v22, v22
	v_add_f32_e32 v24, 1.0, v24
	v_rcp_f32_e32 v24, v24
	v_add_f32_e32 v22, 1.0, v22
	v_rcp_f32_e32 v22, v22
	v_fma_f32 v24, v56, v24, v47
	v_max_f32_e32 v24, 0xda24260, v24
	v_mul_f32_e32 v22, v56, v22
	s_nop 0
	v_log_f32_e32 v24, v24
	s_nop 0
	v_mul_f32_e32 v26, 0x3f317217, v24
	v_fma_f32 v26, v24, s85, -v26
	v_fmac_f32_e32 v26, 0x3377d1cf, v24
	v_fmac_f32_e32 v26, 0x3f317217, v24
	s_nop 1
	v_mov_b32_e32 v24, v26
	v_add_f32_e32 v27, v25, v24
	v_mul_f32_e32 v24, 0xbfb8aa3b, v1
	v_exp_f32_e32 v24, v24
	v_mul_f32_e32 v1, 0x3fb8aa3b, v1
	v_exp_f32_e32 v1, v1
	v_add_f32_e32 v24, 1.0, v24
	v_rcp_f32_e32 v24, v24
	v_add_f32_e32 v1, 1.0, v1
	v_rcp_f32_e32 v1, v1
	v_fma_f32 v24, v56, v24, v47
	v_max_f32_e32 v24, 0xda24260, v24
	s_nop 1
	v_log_f32_e32 v24, v24
	s_nop 0
	v_mul_f32_e32 v26, 0x3f317217, v24
	v_fma_f32 v26, v24, s85, -v26
	v_fmac_f32_e32 v26, 0x3377d1cf, v24
	v_fmac_f32_e32 v26, 0x3f317217, v24
	s_nop 1
	v_mov_b32_e32 v24, v26
	v_add_f32_e32 v28, v27, v24
	v_mul_f32_e32 v24, v56, v1
	v_mul_f32_e32 v1, 0xbfb8aa3b, v0
	v_exp_f32_e32 v1, v1
	v_mul_f32_e32 v0, 0x3fb8aa3b, v0
	v_exp_f32_e32 v0, v0
	v_add_f32_e32 v1, 1.0, v1
	v_rcp_f32_e32 v1, v1
	v_add_f32_e32 v0, 1.0, v0
	v_rcp_f32_e32 v0, v0
	v_fmac_f32_e32 v47, v56, v1
	v_max_f32_e32 v1, 0xda24260, v47
	s_nop 1
	v_log_f32_e32 v1, v1
	s_nop 0
	v_mul_f32_e32 v26, 0x3f317217, v1
	v_fma_f32 v26, v1, s85, -v26
	v_fmac_f32_e32 v26, 0x3377d1cf, v1
	v_fmac_f32_e32 v26, 0x3f317217, v1
	s_nop 1
	v_mov_b32_e32 v1, v26
	v_add_f32_e32 v1, v28, v1
	v_mul_f32_e32 v26, v56, v0
	ds_bpermute_b32 v0, v54, v1
	ds_bpermute_b32 v30, v55, v1
	ds_bpermute_b32 v35, v58, v1
	s_waitcnt lgkmcnt(2)
	v_cndmask_b32_e64 v0, v0, 0, vcc
	s_waitcnt lgkmcnt(1)
	v_cndmask_b32_e64 v30, 0, v30, s[12:13]
	v_add_f32_e32 v0, v0, v30
	s_waitcnt lgkmcnt(0)
	v_cndmask_b32_e64 v30, 0, v35, s[14:15]
	v_add_f32_e32 v0, v0, v30
	v_add_f32_e32 v30, v27, v0
	v_add_f32_e32 v27, v1, v0
	v_add_f32_e32 v35, v25, v0
	v_add_f32_e32 v28, v28, v0
	ds_bpermute_b32 v0, v57, v27
	s_waitcnt lgkmcnt(0)
	v_sub_f32_e32 v25, v0, v30
	v_sub_f32_e32 v1, v0, v35
	v_mul_f32_e32 v25, 0x3fb8aa3b, v25
	v_mul_f32_e32 v1, 0x3fb8aa3b, v1
	v_exp_f32_e32 v25, v25
	v_exp_f32_e32 v1, v1
	v_mul_f32_e32 v25, v22, v25
	v_mul_f32_e32 v1, v20, v1
	v_cvt_pk_bf16_f32 v38, v1, v25
	v_sub_f32_e32 v25, v0, v27
	v_sub_f32_e32 v1, v0, v28
	v_mul_f32_e32 v25, 0x3fb8aa3b, v25
	v_mul_f32_e32 v1, 0x3fb8aa3b, v1
	v_exp_f32_e32 v25, v25
	v_exp_f32_e32 v1, v1
	v_mul_f32_e32 v25, v26, v25
	v_mul_f32_e32 v1, v24, v1
	v_cvt_pk_bf16_f32 v39, v1, v25
	v_add_u32_e32 v25, v53, v60
	ds_write_b64 v59, v[38:39] offset:4608
	s_and_saveexec_b64 s[12:13], vcc
	s_cbranch_execz .LBB0_340
	v_mul_f32_e32 v0, 0x3fb8aa3b, v0
	v_exp_f32_e32 v0, v0
	ds_write_b32 v25, v0 offset:6656

; #define LAS __attribute__((address_space(3)))
; __device__ __forceinline__ unsigned pk2(float lo, float hi) { unsigned r; asm("v_cvt_pk_bf16_f32 %0, %1, %2" : "=v"(r) : "v"(lo), "v"(hi)); return r; }
; __device__ __forceinline__ float fexp(float x) { return __builtin_amdgcn_exp2f(x * LOG2E); }
; __device__ __forceinline__ float sigm(float x) { return frcp(1.f + fexp(-x)); }
; __device__ __forceinline__ void lds_barrier() { asm volatile("s_waitcnt lgkmcnt(0)" ::: "memory"); __builtin_amdgcn_s_barrier(); asm volatile("" ::: "memory"); }
; #define HG_LOAD(n_) do { const size_t T0_ = (size_t)b * SEQ + seg * 128 + (n_) * 16; \
;         _Pragma("unroll") for (int j = 0; j < 4; ++j) { const bf16_t* zp = p.z + (T0_ + fq * 4 + j) * ZLD; qn[j] = zp[768 + kch]; fn[j] = zp[1024 + kch]; vn[j] = zp[1280 + kch]; } } while (0)
; __device__ __forceinline__ void hgrn_item(const Params& p, int l, int item, int pass, LAS unsigned char* lds) {
;     ...
;         if (n < 7) HG_LOAD(n + 1);
;         u32x4 vw; vw.x = vv[0] | (vv[1] << 16); vw.y = vv[2] | (vv[3] << 16); vw.z = 0u; vw.w = 0u; const bf16x8 vfrag = as_bf8(vw);
;         float cs[4], kf[4]; float run = 0.f;
; #pragma unroll
;         for (int j = 0; j < 4; ++j) { const float sg = sigm(fz[j]); const float f = lbv + (1.f - lbv) * sg; run += __logf(fmaxf(f, 1e-30f)); cs[j] = run; kf[j] = (1.f - lbv) * sigm(-fz[j]); }
;         { const float t1 = __shfl(run, lane - 16), t2 = __shfl(run, lane - 32), t3 = __shfl(run, lane - 48);
;           const float pre = (fq >= 1 ? t1 : 0.f) + (fq >= 2 ? t2 : 0.f) + (fq >= 3 ? t3 : 0.f);
; #pragma unroll
;           for (int j = 0; j < 4; ++j) cs[j] += pre; }
;         const float blast = __shfl(cs[3], 48 + fr);
;         lds_barrier();
;         { u32x2 w; w.x = pk2(kf[0] * fexp(blast - cs[0]), kf[1] * fexp(blast - cs[1])); w.y = pk2(kf[2] * fexp(blast - cs[2]), kf[3] * fexp(blast - cs[3]));
;           *(LAS u32x2*)(KHt + (wv * 16 + fr) * 16 + fq * 4) = w;
;           if (fq == 0) decs[wv * 16 + fr] = fexp(blast);
.LBB0_417:
	v_lshl_add_u64 v[50:51], v[22:23], 0, s[28:29]
	v_add_co_u32_e64 v46, s[8:9], s38, v50
	s_waitcnt vmcnt(3)
	v_lshlrev_b32_e32 v56, 16, v48
	v_addc_co_u32_e64 v47, s[8:9], 0, v51, s[8:9]
	global_load_ushort v44, v[46:47], off offset:2048
	global_load_ushort v45, v[46:47], off offset:2560
	v_add_co_u32_e64 v46, s[8:9], s15, v50
	s_waitcnt vmcnt(3)
	v_lshlrev_b32_e32 v57, 16, v49
	v_addc_co_u32_e64 v47, s[8:9], 0, v51, s[8:9]
	v_add_co_u32_e64 v48, s[8:9], s83, v50
	v_lshlrev_b32_e32 v54, 16, v52
	s_nop 0
	v_addc_co_u32_e64 v49, s[8:9], 0, v51, s[8:9]
	v_add_co_u32_e64 v52, s[8:9], s16, v50
	v_lshlrev_b32_e32 v55, 16, v53
	s_nop 0
	v_addc_co_u32_e64 v53, s[8:9], 0, v51, s[8:9]
	global_load_ushort v46, v[46:47], off offset:3584
	s_nop 0
	global_load_ushort v47, v[48:49], off
	s_nop 0
	global_load_ushort v48, v[52:53], off offset:1024
	global_load_ushort v49, v[52:53], off offset:1536
	v_add_co_u32_e64 v52, s[8:9], s14, v50
	s_nop 1
	v_addc_co_u32_e64 v53, s[8:9], 0, v51, s[8:9]
	global_load_ushort v50, v[52:53], off offset:2560
	global_load_ushort v51, v[52:53], off offset:3072
	v_mul_f32_e32 v52, 0xbfb8aa3b, v54
	v_exp_f32_e32 v52, v52
	s_waitcnt lgkmcnt(0)
	s_barrier
	v_add_f32_e32 v52, 1.0, v52
	v_rcp_f32_e32 v52, v52
	s_nop 0
	v_fma_f32 v52, v40, v52, v35
	v_max_f32_e32 v52, 0xda24260, v52
	s_nop 1
	v_log_f32_e32 v52, v52
	s_nop 0
	v_mul_f32_e32 v53, 0x3f317217, v52
	v_fma_f32 v53, v52, s85, -v53
	v_fmac_f32_e32 v53, 0x3377d1cf, v52
	v_fmac_f32_e32 v53, 0x3f317217, v52
	s_nop 1
	v_mov_b32_e32 v52, v53
	v_mul_f32_e32 v53, 0x3fb8aa3b, v54
	v_mul_f32_e32 v54, 0xbfb8aa3b, v55
	v_exp_f32_e32 v54, v54
	v_add_f32_e32 v52, 0, v52
	v_exp_f32_e32 v53, v53
	v_mul_f32_e32 v55, 0x3fb8aa3b, v55
	v_add_f32_e32 v54, 1.0, v54
	v_rcp_f32_e32 v54, v54
	v_add_f32_e32 v53, 1.0, v53
	v_rcp_f32_e32 v53, v53
	v_exp_f32_e32 v55, v55
	v_fma_f32 v54, v40, v54, v35
	v_max_f32_e32 v54, 0xda24260, v54
	v_mul_f32_e32 v53, v40, v53
	v_add_f32_e32 v55, 1.0, v55
	v_log_f32_e32 v54, v54
	v_rcp_f32_e32 v55, v55
	v_mul_f32_e32 v58, 0x3f317217, v54
	v_fma_f32 v58, v54, s85, -v58
	v_fmac_f32_e32 v58, 0x3377d1cf, v54
	v_fmac_f32_e32 v58, 0x3f317217, v54
	v_mul_f32_e32 v55, v40, v55
	s_nop 0
	v_mov_b32_e32 v54, v58
	v_mul_f32_e32 v58, 0xbfb8aa3b, v56
	v_exp_f32_e32 v58, v58
	v_add_f32_e32 v54, v54, v52
	v_mul_f32_e32 v56, 0x3fb8aa3b, v56
	v_exp_f32_e32 v56, v56
	v_add_f32_e32 v58, 1.0, v58
	v_rcp_f32_e32 v58, v58
	v_add_f32_e32 v56, 1.0, v56
	v_rcp_f32_e32 v56, v56
	v_fma_f32 v58, v40, v58, v35
	v_max_f32_e32 v58, 0xda24260, v58
	v_mul_f32_e32 v56, v40, v56
	s_nop 0
	v_log_f32_e32 v58, v58
	s_nop 0
	v_mul_f32_e32 v59, 0x3f317217, v58
	v_fma_f32 v59, v58, s85, -v59
	v_fmac_f32_e32 v59, 0x3377d1cf, v58
	v_fmac_f32_e32 v59, 0x3f317217, v58
	s_nop 1
	v_mov_b32_e32 v58, v59
	v_mul_f32_e32 v59, 0xbfb8aa3b, v57
	v_exp_f32_e32 v59, v59
	v_add_f32_e32 v58, v58, v54
	v_mul_f32_e32 v57, 0x3fb8aa3b, v57
	v_exp_f32_e32 v57, v57
	v_add_f32_e32 v59, 1.0, v59
	v_rcp_f32_e32 v59, v59
	v_add_f32_e32 v57, 1.0, v57
	v_rcp_f32_e32 v57, v57
	v_fma_f32 v59, v40, v59, v35
	v_max_f32_e32 v59, 0xda24260, v59
	v_mul_f32_e32 v57, v40, v57
	s_nop 0
	v_log_f32_e32 v59, v59
	s_nop 0
	v_mul_f32_e32 v60, 0x3f317217, v59
	v_fma_f32 v60, v59, s85, -v60
	v_fmac_f32_e32 v60, 0x3377d1cf, v59
	v_fmac_f32_e32 v60, 0x3f317217, v59
	s_nop 1
	v_mov_b32_e32 v59, v60
	v_add_f32_e32 v59, v59, v58
	ds_bpermute_b32 v60, v38, v59
	ds_bpermute_b32 v61, v39, v59
	ds_bpermute_b32 v62, v37, v59
	s_waitcnt lgkmcnt(2)
	v_cndmask_b32_e64 v60, v60, 0, s[4:5]
	s_waitcnt lgkmcnt(1)
	v_cndmask_b32_e64 v61, 0, v61, s[6:7]
	v_add_f32_e32 v60, v60, v61
	s_waitcnt lgkmcnt(0)
	v_cndmask_b32_e32 v61, 0, v62, vcc
	v_add_f32_e32 v60, v60, v61
	v_add_f32_e32 v59, v59, v60
	v_add_f32_e32 v61, v54, v60
	ds_bpermute_b32 v54, v36, v59
	v_add_f32_e32 v52, v52, v60
	v_add_f32_e32 v58, v58, v60
	s_waitcnt lgkmcnt(0)
	v_sub_f32_e32 v52, v54, v52
	v_mul_f32_e32 v52, 0x3fb8aa3b, v52
	v_exp_f32_e32 v52, v52
	s_nop 0
	v_mul_f32_e32 v52, v53, v52
	v_sub_f32_e32 v53, v54, v61
	v_mul_f32_e32 v53, 0x3fb8aa3b, v53
	v_exp_f32_e32 v53, v53
	s_nop 0
	v_mul_f32_e32 v53, v55, v53
	v_cvt_pk_bf16_f32 v52, v52, v53
	v_sub_f32_e32 v53, v54, v58
	v_mul_f32_e32 v53, 0x3fb8aa3b, v53
	v_sub_f32_e32 v55, v54, v59
	v_exp_f32_e32 v53, v53
	v_mul_f32_e32 v55, 0x3fb8aa3b, v55
	v_exp_f32_e32 v55, v55
	v_mul_f32_e32 v53, v56, v53
	v_mul_f32_e32 v55, v57, v55
	v_cvt_pk_bf16_f32 v53, v53, v55
	ds_write_b64 v34, v[52:53] offset:4608
	s_and_saveexec_b64 s[8:9], s[4:5]
	s_cbranch_execz .LBB0_419
	v_mul_f32_e32 v52, 0x3fb8aa3b, v54
	v_exp_f32_e32 v52, v52
	v_add_u32_e32 v53, v21, v33
	ds_write_b32 v53, v52 offset:6656

; #define LAS __attribute__((address_space(3)))
; __device__ __forceinline__ unsigned pk2(float lo, float hi) { unsigned r; asm("v_cvt_pk_bf16_f32 %0, %1, %2" : "=v"(r) : "v"(lo), "v"(hi)); return r; }
; __device__ __forceinline__ float fexp(float x) { return __builtin_amdgcn_exp2f(x * LOG2E); }
; __device__ __forceinline__ float sigm(float x) { return frcp(1.f + fexp(-x)); }
; __device__ __forceinline__ void lds_barrier() { asm volatile("s_waitcnt lgkmcnt(0)" ::: "memory"); __builtin_amdgcn_s_barrier(); asm volatile("" ::: "memory"); }
; __device__ __forceinline__ void hgrn_item(const Params& p, int l, int item, int pass, LAS unsigned char* lds) {
;     ...
;         for (int j = 0; j < 4; ++j) { const float sg = sigm(fz[j]); const float f = lbv + (1.f - lbv) * sg; run += __logf(fmaxf(f, 1e-30f)); cs[j] = run; kf[j] = (1.f - lbv) * sigm(-fz[j]); }
;         { const float t1 = __shfl(run, lane - 16), t2 = __shfl(run, lane - 32), t3 = __shfl(run, lane - 48);
;           const float pre = (fq >= 1 ? t1 : 0.f) + (fq >= 2 ? t2 : 0.f) + (fq >= 3 ? t3 : 0.f);
; #pragma unroll
;           for (int j = 0; j < 4; ++j) cs[j] += pre; }
;         const float blast = __shfl(cs[3], 48 + fr);
;         lds_barrier();
;         { u32x2 w; w.x = pk2(kf[0] * fexp(blast - cs[0]), kf[1] * fexp(blast - cs[1])); w.y = pk2(kf[2] * fexp(blast - cs[2]), kf[3] * fexp(blast - cs[3]));
;           *(LAS u32x2*)(KHt + (wv * 16 + fr) * 16 + fq * 4) = w;
;           if (fq == 0) decs[wv * 16 + fr] = fexp(blast);
.LBB0_421:
	v_lshlrev_b32_e32 v22, 16, v52
	v_mul_f32_e32 v23, 0xbfb8aa3b, v22
	v_exp_f32_e32 v23, v23
	v_mul_f32_e32 v22, 0x3fb8aa3b, v22
	v_exp_f32_e32 v22, v22
	v_lshlrev_b32_e32 v3, 16, v53
	v_add_f32_e32 v23, 1.0, v23
	v_rcp_f32_e32 v23, v23
	v_add_f32_e32 v22, 1.0, v22
	v_rcp_f32_e32 v22, v22
	v_lshlrev_b32_e32 v1, 16, v48
	v_fma_f32 v23, v40, v23, v35
	v_max_f32_e32 v23, 0xda24260, v23
	v_lshlrev_b32_e32 v0, 16, v49
	s_waitcnt lgkmcnt(0)
	s_barrier
	v_log_f32_e32 v23, v23
	s_nop 0
	v_mul_f32_e32 v42, 0x3f317217, v23
	v_fma_f32 v42, v23, s85, -v42
	v_fmac_f32_e32 v42, 0x3377d1cf, v23
	v_fmac_f32_e32 v42, 0x3f317217, v23
	s_nop 1
	v_mov_b32_e32 v23, v42
	v_mul_f32_e32 v42, v40, v22
	v_mul_f32_e32 v22, 0xbfb8aa3b, v3
	v_exp_f32_e32 v22, v22
	v_mul_f32_e32 v3, 0x3fb8aa3b, v3
	v_exp_f32_e32 v3, v3
	v_add_f32_e32 v23, 0, v23
	v_add_f32_e32 v22, 1.0, v22
	v_rcp_f32_e32 v22, v22
	v_add_f32_e32 v3, 1.0, v3
	v_rcp_f32_e32 v3, v3
	v_fma_f32 v22, v40, v22, v35
	v_max_f32_e32 v22, 0xda24260, v22
	v_mul_f32_e32 v3, v40, v3
	s_nop 0
	v_log_f32_e32 v22, v22
	s_nop 0
	v_mul_f32_e32 v43, 0x3f317217, v22
	v_fma_f32 v43, v22, s85, -v43
	v_fmac_f32_e32 v43, 0x3377d1cf, v22
	v_fmac_f32_e32 v43, 0x3f317217, v22
	s_nop 1
	v_mov_b32_e32 v22, v43
	v_mul_f32_e32 v43, 0xbfb8aa3b, v1
	v_exp_f32_e32 v43, v43
	v_mul_f32_e32 v1, 0x3fb8aa3b, v1
	v_exp_f32_e32 v1, v1
	v_add_f32_e32 v22, v23, v22
	v_add_f32_e32 v43, 1.0, v43
	v_rcp_f32_e32 v43, v43
	v_add_f32_e32 v1, 1.0, v1
	v_rcp_f32_e32 v1, v1
	v_fma_f32 v43, v40, v43, v35
	v_max_f32_e32 v43, 0xda24260, v43
	v_mul_f32_e32 v1, v40, v1
	s_nop 0
	v_log_f32_e32 v43, v43
	s_nop 0
	v_mul_f32_e32 v48, 0x3f317217, v43
	v_fma_f32 v48, v43, s85, -v48
	v_fmac_f32_e32 v48, 0x3377d1cf, v43
	v_fmac_f32_e32 v48, 0x3f317217, v43
	s_nop 1
	v_mov_b32_e32 v43, v48
	v_mul_f32_e32 v48, 0xbfb8aa3b, v0
	v_exp_f32_e32 v48, v48
	v_mul_f32_e32 v0, 0x3fb8aa3b, v0
	v_exp_f32_e32 v0, v0
	v_add_f32_e32 v43, v22, v43
	v_add_f32_e32 v48, 1.0, v48
	v_rcp_f32_e32 v48, v48
	v_add_f32_e32 v0, 1.0, v0
	v_rcp_f32_e32 v0, v0
	v_fmac_f32_e32 v35, v40, v48
	v_max_f32_e32 v35, 0xda24260, v35
	v_mul_f32_e32 v40, v40, v0
	s_nop 0
	v_log_f32_e32 v35, v35
	s_nop 0
	v_mul_f32_e32 v48, 0x3f317217, v35
	v_fma_f32 v48, v35, s85, -v48
	v_fmac_f32_e32 v48, 0x3377d1cf, v35
	v_fmac_f32_e32 v48, 0x3f317217, v35
	s_nop 1
	v_mov_b32_e32 v35, v48
	v_add_f32_e32 v35, v43, v35
	ds_bpermute_b32 v0, v38, v35
	ds_bpermute_b32 v38, v39, v35
	ds_bpermute_b32 v37, v37, v35
	s_waitcnt lgkmcnt(2)
	v_cndmask_b32_e64 v0, v0, 0, s[4:5]
	s_waitcnt lgkmcnt(1)
	v_cndmask_b32_e64 v38, 0, v38, s[6:7]
	v_add_f32_e32 v0, v0, v38
	s_waitcnt lgkmcnt(0)
	v_cndmask_b32_e32 v37, 0, v37, vcc
	v_add_f32_e32 v0, v0, v37
	v_add_f32_e32 v35, v35, v0
	v_add_f32_e32 v37, v22, v0
	ds_bpermute_b32 v22, v36, v35
	v_add_f32_e32 v23, v23, v0
	v_add_f32_e32 v38, v43, v0
	s_waitcnt lgkmcnt(0)
	v_sub_f32_e32 v0, v22, v23
	v_sub_f32_e32 v23, v22, v37
	v_mul_f32_e32 v0, 0x3fb8aa3b, v0
	v_mul_f32_e32 v23, 0x3fb8aa3b, v23
	v_exp_f32_e32 v0, v0
	v_exp_f32_e32 v23, v23
	v_mul_f32_e32 v0, v42, v0
	v_mul_f32_e32 v3, v3, v23
	v_cvt_pk_bf16_f32 v0, v0, v3
	v_sub_f32_e32 v3, v22, v38
	v_mul_f32_e32 v3, 0x3fb8aa3b, v3
	v_exp_f32_e32 v3, v3
	s_nop 0
	v_mul_f32_e32 v1, v1, v3
	v_sub_f32_e32 v3, v22, v35
	v_mul_f32_e32 v3, 0x3fb8aa3b, v3
	v_exp_f32_e32 v3, v3
	s_nop 0
	v_mul_f32_e32 v3, v40, v3
	v_cvt_pk_bf16_f32 v1, v1, v3
	ds_write_b64 v34, v[0:1] offset:4608
	s_and_saveexec_b64 s[6:7], s[4:5]
	s_cbranch_execz .LBB0_423
	v_mul_f32_e32 v0, 0x3fb8aa3b, v22
	v_exp_f32_e32 v0, v0
	v_add_u32_e32 v1, v21, v33
	ds_write_b32 v1, v0 offset:6656
